# attention: first two P.V MFMAs of each step inside the previous step's pack tail, the other six spread over the row-max region
# speedup vs baseline: 1.0086x; 1.0019x over previous
.LBB0_999:
	v_mfma_f32_32x32x16_bf16 v[4:19], v[80:83], v[180:183], v[4:19]
	v_lshl_add_u64 v[84:85], s[48:49], 0, v[190:191]
	s_cselect_b32 s49, s49, s51
	s_cselect_b32 s48, s48, s50
	s_cselect_b32 s43, s38, s40
	global_load_lds_dwordx4 v[84:85], off
	v_lshl_add_u64 v[84:85], s[48:49], 0, v[192:193]
	s_add_i32 m0, s21, s43
	s_add_i32 s43, s23, s40
	global_load_lds_dwordx4 v[84:85], off
	v_lshl_add_u64 v[84:85], s[50:51], 0, v[194:195]
	s_add_i32 m0, s43, 0xd000
	s_mov_b32 s43, s39
	global_load_lds_dwordx4 v[84:85], off
	s_mov_b32 s39, s44
	s_mov_b32 s44, s15
	s_mov_b32 s45, s14
	v_max3_f32 v2, v52, v36, v53
	s_nop 0
	v_max3_f32 v2, v2, v37, v54
	v_mfma_f32_32x32x16_bf16 v[20:35], v[80:83], v[164:167], v[20:35]
	s_nop 0
	v_max3_f32 v2, v2, v38, v55
	s_nop 0
	v_max3_f32 v2, v2, v39, v56
	v_max3_f32 v68, v60, v44, v61
	v_max3_f32 v2, v2, v40, v57
	v_mfma_f32_32x32x16_bf16 v[4:19], v[76:79], v[176:179], v[4:19]
	s_nop 0
	v_max3_f32 v68, v68, v45, v62
	v_max3_f32 v2, v2, v41, v58
	s_nop 0
	v_max3_f32 v68, v68, v46, v63
	v_max3_f32 v68, v68, v47, v64
	v_mfma_f32_32x32x16_bf16 v[20:35], v[76:79], v[156:159], v[20:35]
	v_max3_f32 v2, v2, v42, v59
	v_max3_f32 v68, v68, v48, v65
	s_nop 0
	v_max3_f32 v68, v68, v49, v66
	v_max3_f32 v68, v68, v50, v67
	s_nop 0
	v_mfma_f32_32x32x16_bf16 v[20:35], v[72:75], v[152:155], v[20:35]
	v_max3_f32 v2, v2, v43, v68
	s_nop 0
	v_max3_f32 v2, v2, v51, v2
	s_nop 0
	v_mov_b32_e32 v68, v2
	v_mov_b32_e32 v69, v2
	v_mfma_f32_32x32x16_bf16 v[4:19], v[72:75], v[148:151], v[4:19]
	s_nop 1
	v_permlane32_swap_b32_e32 v68, v69
	v_max3_f32 v2, v68, v69, v2
	s_nop 0
	v_cmp_lt_f32_e32 vcc, s56, v2
	s_cbranch_vccz .LBB0_1003
	v_add_f32_e32 v180, v210, v2
	v_cvt_pk_bf16_f32 v180, v180, v180
	v_lshlrev_b32_e32 v180, 16, v180
	v_cndmask_b32_e32 v180, v210, v180, vcc
	v_sub_f32_e32 v2, v210, v180
	v_sub_f32_e32 v84, v180, v210
	v_xor_b32_e32 v250, 0x80000000, v180
	v_min_f32_e32 v2, 0, v2
	v_lshrrev_b32_e32 v250, 16, v250
	v_exp_f32_e32 v2, v2
	v_cndmask_b32_e64 v250, 0, v250, s[2:3]
	s_and_saveexec_b64 s[14:15], s[2:3]
	ds_write_b32 v202, v2
	s_or_b64 exec, exec, s[14:15]
	ds_read_b32 v68, v1
	ds_read_b32 v69, v1 offset:4
	ds_read_b32 v70, v1 offset:8
	ds_read_b32 v71, v1 offset:12
	ds_read_b32 v72, v1 offset:32
	ds_read_b32 v73, v1 offset:36
	ds_read_b32 v74, v1 offset:40
	ds_read_b32 v75, v1 offset:44
	ds_read_b32 v76, v1 offset:64
	ds_read_b32 v77, v1 offset:68
	ds_read_b32 v78, v1 offset:72
	ds_read_b32 v79, v1 offset:76
	ds_read_b32 v80, v1 offset:96
	ds_read_b32 v81, v1 offset:100
	ds_read_b32 v82, v1 offset:104
	ds_read_b32 v83, v1 offset:108
	v_mul_f32_e32 v209, v209, v2
	s_waitcnt lgkmcnt(0)
	v_pk_mul_f32 v[20:21], v[20:21], v[68:69]
	v_pk_mul_f32 v[22:23], v[22:23], v[70:71]
	v_pk_mul_f32 v[24:25], v[24:25], v[72:73]
	v_pk_mul_f32 v[26:27], v[26:27], v[74:75]
	v_pk_mul_f32 v[28:29], v[28:29], v[76:77]
	v_pk_mul_f32 v[30:31], v[30:31], v[78:79]
	v_pk_mul_f32 v[32:33], v[32:33], v[80:81]
	v_pk_mul_f32 v[34:35], v[34:35], v[82:83]
	v_pk_mul_f32 v[4:5], v[4:5], v[68:69]
	v_pk_mul_f32 v[6:7], v[6:7], v[70:71]
	v_pk_mul_f32 v[8:9], v[8:9], v[72:73]
	v_pk_mul_f32 v[10:11], v[10:11], v[74:75]
	v_pk_mul_f32 v[12:13], v[12:13], v[76:77]
	v_pk_mul_f32 v[14:15], v[14:15], v[78:79]
	v_pk_mul_f32 v[16:17], v[16:17], v[80:81]
	v_pk_mul_f32 v[18:19], v[18:19], v[82:83]
	v_sub_f32_e32 v36, v36, v84
	v_sub_f32_e32 v37, v37, v84
	v_sub_f32_e32 v38, v38, v84
	v_sub_f32_e32 v39, v39, v84
	v_sub_f32_e32 v40, v40, v84
	v_sub_f32_e32 v41, v41, v84
	v_sub_f32_e32 v42, v42, v84
	v_sub_f32_e32 v43, v43, v84
	v_sub_f32_e32 v44, v44, v84
	v_sub_f32_e32 v45, v45, v84
	v_sub_f32_e32 v46, v46, v84
	v_sub_f32_e32 v47, v47, v84
	v_sub_f32_e32 v48, v48, v84
	v_sub_f32_e32 v49, v49, v84
	v_sub_f32_e32 v50, v50, v84
	v_sub_f32_e32 v51, v51, v84
	v_sub_f32_e32 v52, v52, v84
	v_sub_f32_e32 v53, v53, v84
	v_sub_f32_e32 v54, v54, v84
	v_sub_f32_e32 v55, v55, v84
	v_sub_f32_e32 v56, v56, v84
	v_sub_f32_e32 v57, v57, v84
	v_sub_f32_e32 v58, v58, v84
	v_sub_f32_e32 v59, v59, v84
	v_sub_f32_e32 v60, v60, v84
	v_sub_f32_e32 v61, v61, v84
	v_sub_f32_e32 v62, v62, v84
	v_sub_f32_e32 v63, v63, v84
	v_sub_f32_e32 v64, v64, v84
	v_sub_f32_e32 v65, v65, v84
	v_sub_f32_e32 v66, v66, v84
	v_sub_f32_e32 v67, v67, v84
	s_mov_b32 s56, 0x41000000
	s_branch .LBB0_1004

.LBB0_1004:
	v_mfma_f32_32x32x16_bf16 v[68:83], v[246:249], v[250:253], 0
	v_mfma_f32_32x32x16_bf16 v[68:83], v[136:139], v[100:103], v[68:83]
	v_add_u32_e32 v2, s45, v189
	ds_read_b128 v[184:187], v2 offset:96
	ds_read_b128 v[210:213], v2 offset:128
	ds_read_b128 v[214:217], v2 offset:6752
	ds_read_b128 v[218:221], v2 offset:160
	ds_read_b128 v[222:225], v2 offset:6784
	ds_read_b128 v[226:229], v2 offset:6816
	v_add_u32_e32 v2, s39, v200
	ds_read_b128 v[176:179], v2 offset:53248
	ds_read_b128 v[164:167], v2 offset:53280
	ds_read_b128 v[230:233], v2 offset:57856
	ds_read_b128 v[238:241], v2 offset:57888
	ds_read_b128 v[160:163], v2 offset:53312
	ds_read_b128 v[156:159], v2 offset:53344
	ds_read_b128 v[242:245], v2 offset:57920
	ds_read_b128 v[152:155], v2 offset:57952
	v_mfma_f32_32x32x16_bf16 v[84:99], v[246:249], v[250:253], 0
	v_mfma_f32_32x32x16_bf16 v[84:99], v[132:135], v[100:103], v[84:99]
	v_exp_f32_e32 v52, v52
	v_exp_f32_e32 v183, v36
	v_exp_f32_e32 v132, v53
	v_exp_f32_e32 v53, v54
	v_mfma_f32_32x32x16_bf16 v[68:83], v[144:147], v[104:107], v[68:83]
	v_exp_f32_e32 v54, v38
	v_exp_f32_e32 v36, v55
	v_exp_f32_e32 v55, v56
	v_exp_f32_e32 v56, v40
	v_mfma_f32_32x32x16_bf16 v[84:99], v[128:131], v[104:107], v[84:99]
	v_exp_f32_e32 v40, v39
	v_exp_f32_e32 v38, v57
	v_exp_f32_e32 v57, v58
	v_exp_f32_e32 v58, v41
	v_mfma_f32_32x32x16_bf16 v[68:83], v[140:143], v[108:111], v[68:83]
	v_add_u32_e32 v181, s44, v189
	ds_read_b128 v[144:147], v181
	ds_read_b128 v[172:175], v181 offset:32
	ds_read_b128 v[136:139], v181 offset:6656
	ds_read_b128 v[168:171], v181 offset:64
	ds_read_b128 v[148:151], v181 offset:6688
	ds_read_b128 v[140:143], v181 offset:6720
	v_exp_f32_e32 v2, v37
	v_mfma_f32_32x32x16_bf16 v[84:99], v[124:127], v[108:111], v[84:99]
	v_exp_f32_e32 v124, v59
	v_exp_f32_e32 v41, v60
	v_add_f32_e32 v133, v52, v183
	v_add_f32_e32 v37, v53, v54
	s_waitcnt lgkmcnt(14)
	v_mfma_f32_32x32x16_bf16 v[68:83], v[214:217], v[112:115], v[68:83]
	v_exp_f32_e32 v214, v42
	v_exp_f32_e32 v59, v44
	v_exp_f32_e32 v60, v43
	v_exp_f32_e32 v126, v61
	v_mfma_f32_32x32x16_bf16 v[84:99], v[184:187], v[112:115], v[84:99]
	v_exp_f32_e32 v61, v62
	v_exp_f32_e32 v62, v45
	v_exp_f32_e32 v128, v63
	v_exp_f32_e32 v63, v64
	v_mfma_f32_32x32x16_bf16 v[68:83], v[222:225], v[116:119], v[68:83]
	v_exp_f32_e32 v216, v48
	v_exp_f32_e32 v64, v47
	v_exp_f32_e32 v130, v65
	v_mfma_f32_32x32x16_bf16 v[84:99], v[210:213], v[116:119], v[84:99]
	v_exp_f32_e32 v65, v66
	v_exp_f32_e32 v215, v46
	v_exp_f32_e32 v185, v50
	v_mfma_f32_32x32x16_bf16 v[68:83], v[226:229], v[120:123], v[68:83]
	v_exp_f32_e32 v66, v49
	v_exp_f32_e32 v134, v67
	v_add_f32_e32 v39, v55, v56
	v_add_f32_e32 v125, v57, v214
	v_mfma_f32_32x32x16_bf16 v[84:99], v[218:221], v[120:123], v[84:99]
	v_add_f32_e32 v127, v41, v59
	v_add_f32_e32 v129, v61, v215
	v_add_f32_e32 v131, v63, v216
	v_add_f32_e32 v135, v65, v185
	v_exp_f32_e32 v184, v51
	v_cvt_pk_bf16_f32 v42, v52, v132
	v_cvt_pk_bf16_f32 v43, v53, v36
	v_cvt_pk_bf16_f32 v44, v55, v38
	v_cvt_pk_bf16_f32 v45, v57, v124
	v_cvt_pk_bf16_f32 v46, v41, v126
	v_cvt_pk_bf16_f32 v47, v61, v128
	s_waitcnt lgkmcnt(0)
	v_mfma_f32_32x32x16_bf16 v[4:19], v[42:45], v[230:233], v[4:19]
	v_cvt_pk_bf16_f32 v48, v63, v130
	v_cvt_pk_bf16_f32 v49, v65, v134
	v_cvt_pk_bf16_f32 v50, v183, v2
	v_cvt_pk_bf16_f32 v51, v54, v40
	v_cvt_pk_bf16_f32 v52, v56, v58
	v_cvt_pk_bf16_f32 v53, v214, v60
	v_mfma_f32_32x32x16_bf16 v[20:35], v[42:45], v[176:179], v[20:35]
	v_cvt_pk_bf16_f32 v54, v59, v62
	v_cvt_pk_bf16_f32 v55, v215, v64
	v_cvt_pk_bf16_f32 v56, v216, v66
	v_cvt_pk_bf16_f32 v57, v185, v184
	s_add_i32 s14, s46, 5
	s_min_u32 s14, s14, s37
	s_add_i32 s15, s46, 3
	s_min_u32 s46, s15, s37
	s_mulk_i32 s14, 0x3000
	s_add_u32 s14, s10, s14
	s_addc_u32 s15, s11, 0
	s_lshl_b32 s46, s46, 13
	s_add_u32 s46, s12, s46
	s_addc_u32 s47, s13, 0
	s_add_i32 m0, s22, s45
	s_and_b64 s[48:49], s[4:5], exec
	s_waitcnt vmcnt(3) lgkmcnt(0)
	s_barrier
	v_mfma_f32_32x32x16_bf16 v[4:19], v[46:49], v[238:241], v[4:19]
	v_lshl_add_u64 v[186:187], s[14:15], 0, v[190:191]
	s_cselect_b32 s15, s15, s47
	s_cselect_b32 s14, s14, s46
	global_load_lds_dwordx4 v[186:187], off
	v_lshl_add_u64 v[186:187], s[14:15], 0, v[192:193]
	s_cselect_b32 s14, s45, s39
	s_add_i32 m0, s21, s14
	s_add_i32 s14, s23, s39
	global_load_lds_dwordx4 v[186:187], off
	v_lshl_add_u64 v[186:187], s[46:47], 0, v[194:195]
	s_add_i32 m0, s14, 0xd000
	s_nop 0
	global_load_lds_dwordx4 v[186:187], off
	v_max3_f32 v41, v84, v68, v85
	v_max3_f32 v59, v92, v76, v93
	v_add_f32_e32 v132, v132, v2
	v_max3_f32 v41, v41, v69, v86
	v_max3_f32 v59, v59, v77, v94
	v_mfma_f32_32x32x16_bf16 v[20:35], v[46:49], v[164:167], v[20:35]
	s_nop 0
	v_max3_f32 v41, v41, v70, v87
	v_max3_f32 v41, v41, v71, v88
	v_max3_f32 v59, v59, v78, v95
	v_max3_f32 v41, v41, v72, v89
	v_max3_f32 v59, v59, v79, v96
	s_nop 0
	v_max3_f32 v41, v41, v73, v90
	v_max3_f32 v183, v41, v74, v91
	v_mfma_f32_32x32x16_bf16 v[4:19], v[50:53], v[242:245], v[4:19]
	v_add_f32_e32 v41, v132, v133
	v_max3_f32 v59, v59, v80, v97
	v_add_f32_e64 v36, v36, v40
	v_add_f32_e64 v37, v37, v41
	v_max3_f32 v59, v59, v81, v98
	v_max3_f32 v186, v59, v82, v99
	v_add_f32_e32 v59, v36, v37
	v_add_f32_e32 v36, v38, v58
	v_add_f32_e32 v37, v39, v59
	v_mfma_f32_32x32x16_bf16 v[20:35], v[50:53], v[160:163], v[20:35]
	v_add_f32_e32 v61, v36, v37
	v_add_f32_e32 v36, v124, v60
	v_add_f32_e32 v37, v125, v61
	v_add_f32_e32 v63, v36, v37
	v_add_f32_e32 v36, v126, v62
	v_add_f32_e32 v37, v127, v63
	v_add_f32_e32 v65, v36, v37
	v_add_f32_e32 v36, v128, v64
	v_add_f32_e32 v37, v129, v65
	v_mfma_f32_32x32x16_bf16 v[20:35], v[54:57], v[156:159], v[20:35]
	v_add_f32_e32 v67, v36, v37
	v_add_f32_e32 v36, v130, v66
	v_add_f32_e32 v37, v131, v67
	v_add_f32_e32 v185, v36, v37
	v_add_f32_e32 v36, v134, v184
	v_add_f32_e32 v37, v135, v185
	v_add_f32_e32 v2, v36, v37
	v_max3_f32 v36, v183, v75, v186
	v_add_f32_e32 v2, v209, v2
	v_mfma_f32_32x32x16_bf16 v[4:19], v[54:57], v[152:155], v[4:19]
	v_max3_f32 v36, v36, v83, v36
	s_nop 0
	v_mov_b32_e32 v37, v36
	v_mov_b32_e32 v38, v36
	s_nop 0
	v_permlane32_swap_b32_e32 v37, v38
	v_max3_f32 v36, v37, v38, v36
	s_nop 0
	v_cmp_lt_f32_e32 vcc, s56, v36
	s_cbranch_vccz .LBB0_1008
	s_nop 0
	v_add_f32_e32 v210, v180, v36
	v_cvt_pk_bf16_f32 v210, v210, v210
	v_lshlrev_b32_e32 v210, 16, v210
	v_cndmask_b32_e32 v210, v180, v210, vcc
	v_sub_f32_e32 v36, v180, v210
	v_sub_f32_e32 v186, v210, v180
	v_xor_b32_e32 v250, 0x80000000, v210
	v_min_f32_e32 v36, 0, v36
	v_lshrrev_b32_e32 v250, 16, v250
	v_exp_f32_e32 v36, v36
	v_cndmask_b32_e64 v250, 0, v250, s[2:3]
	s_and_saveexec_b64 s[14:15], s[2:3]
	ds_write_b32 v202, v36
	s_or_b64 exec, exec, s[14:15]
	v_mul_f32_e32 v2, v2, v36
	ds_read_b32 v36, v1
	ds_read_b32 v37, v1 offset:4
	ds_read_b32 v38, v1 offset:8
	ds_read_b32 v39, v1 offset:12
	ds_read_b32 v40, v1 offset:32
	ds_read_b32 v41, v1 offset:36
	ds_read_b32 v42, v1 offset:40
	ds_read_b32 v43, v1 offset:44
	ds_read_b32 v44, v1 offset:64
	ds_read_b32 v45, v1 offset:68
	ds_read_b32 v46, v1 offset:72
	ds_read_b32 v47, v1 offset:76
	ds_read_b32 v48, v1 offset:96
	ds_read_b32 v49, v1 offset:100
	ds_read_b32 v50, v1 offset:104
	ds_read_b32 v51, v1 offset:108
	s_waitcnt lgkmcnt(0)
	v_pk_mul_f32 v[20:21], v[20:21], v[36:37]
	v_pk_mul_f32 v[22:23], v[22:23], v[38:39]
	v_pk_mul_f32 v[24:25], v[24:25], v[40:41]
	v_pk_mul_f32 v[26:27], v[26:27], v[42:43]
	v_pk_mul_f32 v[28:29], v[28:29], v[44:45]
	v_pk_mul_f32 v[30:31], v[30:31], v[46:47]
	v_pk_mul_f32 v[32:33], v[32:33], v[48:49]
	v_pk_mul_f32 v[34:35], v[34:35], v[50:51]
	v_pk_mul_f32 v[4:5], v[4:5], v[36:37]
	v_pk_mul_f32 v[6:7], v[6:7], v[38:39]
	v_pk_mul_f32 v[8:9], v[8:9], v[40:41]
	v_pk_mul_f32 v[10:11], v[10:11], v[42:43]
	v_pk_mul_f32 v[12:13], v[12:13], v[44:45]
	v_pk_mul_f32 v[14:15], v[14:15], v[46:47]
	v_pk_mul_f32 v[16:17], v[16:17], v[48:49]
	v_pk_mul_f32 v[18:19], v[18:19], v[50:51]
	v_sub_f32_e32 v68, v68, v186
	v_sub_f32_e32 v69, v69, v186
	v_sub_f32_e32 v70, v70, v186
	v_sub_f32_e32 v71, v71, v186
	v_sub_f32_e32 v72, v72, v186
	v_sub_f32_e32 v73, v73, v186
	v_sub_f32_e32 v74, v74, v186
	v_sub_f32_e32 v75, v75, v186
	v_sub_f32_e32 v76, v76, v186
	v_sub_f32_e32 v77, v77, v186
	v_sub_f32_e32 v78, v78, v186
	v_sub_f32_e32 v79, v79, v186
	v_sub_f32_e32 v80, v80, v186
	v_sub_f32_e32 v81, v81, v186
	v_sub_f32_e32 v82, v82, v186
	v_sub_f32_e32 v83, v83, v186
	v_sub_f32_e32 v84, v84, v186
	v_sub_f32_e32 v85, v85, v186
	v_sub_f32_e32 v86, v86, v186
	v_sub_f32_e32 v87, v87, v186
	v_sub_f32_e32 v88, v88, v186
	v_sub_f32_e32 v89, v89, v186
	v_sub_f32_e32 v90, v90, v186
	v_sub_f32_e32 v91, v91, v186
	v_sub_f32_e32 v92, v92, v186
	v_sub_f32_e32 v93, v93, v186
	v_sub_f32_e32 v94, v94, v186
	v_sub_f32_e32 v95, v95, v186
	v_sub_f32_e32 v96, v96, v186
	v_sub_f32_e32 v97, v97, v186
	v_sub_f32_e32 v98, v98, v186
	v_sub_f32_e32 v99, v99, v186
	s_mov_b32 s56, 0x41000000
	s_branch .LBB0_1009

; __device__ __forceinline__ void ph_attn(Frame& F) {
;     ...
;         for (int t = 0; t < NT; t += 2) {
;             AT_STEP(pA0, pA1, pB0, pB1, t);
;             AT_STEP(pB0, pB1, pA0, pA1, t + 1);
;         }
.LBB0_1009:
	v_mfma_f32_32x32x16_bf16 v[36:51], v[246:249], v[250:253], 0
	v_mfma_f32_32x32x16_bf16 v[36:51], v[136:139], v[100:103], v[36:51]
	v_add_u32_e32 v52, s43, v200
	ds_read_b128 v[212:215], v181 offset:96
	ds_read_b128 v[216:219], v181 offset:128
	ds_read_b128 v[220:223], v181 offset:6752
	ds_read_b128 v[224:227], v181 offset:160
	ds_read_b128 v[228:231], v181 offset:6784
	ds_read_b128 v[238:241], v181 offset:6816
	ds_read_b128 v[160:163], v52 offset:53248
	ds_read_b128 v[164:167], v52 offset:53280
	ds_read_b128 v[184:187], v52 offset:57856
	ds_read_b128 v[180:183], v52 offset:57888
	ds_read_b128 v[156:159], v52 offset:53312
	ds_read_b128 v[152:155], v52 offset:53344
	v_add_u32_e32 v209, s41, v189
	v_mfma_f32_32x32x16_bf16 v[36:51], v[148:151], v[104:107], v[36:51]
	ds_read_b128 v[176:179], v52 offset:57920
	ds_read_b128 v[148:151], v52 offset:57952
	v_exp_f32_e32 v211, v84
	v_exp_f32_e32 v232, v68
	v_exp_f32_e32 v233, v85
	v_mfma_f32_32x32x16_bf16 v[52:67], v[246:249], v[250:253], 0
	v_mfma_f32_32x32x16_bf16 v[52:67], v[144:147], v[100:103], v[52:67]
	v_exp_f32_e32 v235, v69
	v_add_f32_e32 v68, v211, v232
	v_add_f32_e32 v69, v233, v235
	v_add_f32_e32 v68, v69, v68
	v_mfma_f32_32x32x16_bf16 v[52:67], v[172:175], v[104:107], v[52:67]
	v_exp_f32_e32 v173, v70
	v_exp_f32_e32 v172, v86
	v_exp_f32_e32 v174, v87
	v_exp_f32_e32 v175, v71
	v_add_f32_e32 v69, v172, v173
	v_add_f32_e32 v68, v69, v68
	v_mfma_f32_32x32x16_bf16 v[52:67], v[168:171], v[108:111], v[52:67]
	v_add_f32_e32 v69, v174, v175
	v_add_f32_e32 v168, v69, v68
	v_exp_f32_e32 v71, v88
	v_exp_f32_e32 v85, v72
	v_exp_f32_e32 v70, v89
	v_exp_f32_e32 v84, v73
	v_exp_f32_e32 v73, v90
	v_exp_f32_e32 v87, v74
	v_exp_f32_e32 v72, v91
	v_exp_f32_e32 v86, v75
	v_pk_add_f32 v[68:69], v[70:71], v[84:85]
	v_mfma_f32_32x32x16_bf16 v[36:51], v[140:143], v[108:111], v[36:51]
	v_add_f32_e32 v69, v69, v168
	v_add_f32_e32 v74, v68, v69
	v_add_f32_e64 v68, v72, v86
	v_add_f32_e64 v69, v73, v87
	ds_read_b128 v[132:135], v209
	ds_read_b128 v[128:131], v209 offset:32
	ds_read_b128 v[136:139], v209 offset:6656
	ds_read_b128 v[124:127], v209 offset:64
	v_add_f32_e32 v69, v69, v74
	v_add_f32_e32 v168, v68, v69
	v_exp_f32_e32 v75, v92
	v_exp_f32_e32 v89, v76
	v_exp_f32_e32 v74, v93
	v_exp_f32_e32 v88, v77
	v_exp_f32_e32 v77, v94
	s_waitcnt lgkmcnt(12)
	v_mfma_f32_32x32x16_bf16 v[36:51], v[220:223], v[112:115], v[36:51]
	v_exp_f32_e32 v91, v78
	v_exp_f32_e32 v76, v95
	v_exp_f32_e32 v90, v79
	v_pk_add_f32 v[68:69], v[74:75], v[88:89]
	ds_read_b128 v[144:147], v209 offset:6688
	ds_read_b128 v[140:143], v209 offset:6720
	v_mfma_f32_32x32x16_bf16 v[52:67], v[212:215], v[112:115], v[52:67]
	v_add_f32_e32 v69, v69, v168
	v_add_f32_e32 v78, v68, v69
	v_add_f32_e64 v68, v76, v90
	v_add_f32_e64 v69, v77, v91
	v_add_f32_e32 v69, v69, v78
	v_add_f32_e32 v168, v68, v69
	v_mfma_f32_32x32x16_bf16 v[36:51], v[228:231], v[116:119], v[36:51]
	v_exp_f32_e32 v79, v96
	v_exp_f32_e32 v93, v80
	v_exp_f32_e32 v78, v97
	v_exp_f32_e32 v92, v81
	v_mfma_f32_32x32x16_bf16 v[52:67], v[216:219], v[116:119], v[52:67]
	v_exp_f32_e32 v95, v98
	v_exp_f32_e32 v97, v82
	v_exp_f32_e32 v94, v99
	v_mfma_f32_32x32x16_bf16 v[36:51], v[238:241], v[120:123], v[36:51]
	v_exp_f32_e32 v96, v83
	v_pk_add_f32 v[68:69], v[78:79], v[92:93]
	s_nop 0
	v_add_f32_e32 v69, v69, v168
	v_add_f32_e32 v80, v68, v69
	v_pk_add_f32 v[68:69], v[94:95], v[96:97]
	v_mfma_f32_32x32x16_bf16 v[52:67], v[224:227], v[120:123], v[52:67]
	v_add_f32_e32 v69, v69, v80
	v_add_f32_e32 v68, v68, v69
	v_add_f32_e32 v209, v2, v68
	v_cvt_pk_bf16_f32 v68, v211, v233
	v_cvt_pk_bf16_f32 v69, v172, v174
	v_cvt_pk_bf16_f32 v70, v71, v70
	v_cvt_pk_bf16_f32 v71, v73, v72
	v_cvt_pk_bf16_f32 v80, v75, v74
	v_cvt_pk_bf16_f32 v81, v77, v76
	s_waitcnt lgkmcnt(0)
	v_mfma_f32_32x32x16_bf16 v[4:19], v[68:71], v[184:187], v[4:19]
	v_cvt_pk_bf16_f32 v82, v79, v78
	v_cvt_pk_bf16_f32 v83, v95, v94
	v_cvt_pk_bf16_f32 v76, v232, v235
	v_cvt_pk_bf16_f32 v77, v173, v175
	v_cvt_pk_bf16_f32 v78, v85, v84
	v_cvt_pk_bf16_f32 v79, v87, v86
	v_mfma_f32_32x32x16_bf16 v[20:35], v[68:71], v[160:163], v[20:35]
	v_cvt_pk_bf16_f32 v72, v89, v88
	v_cvt_pk_bf16_f32 v73, v91, v90
	v_cvt_pk_bf16_f32 v74, v93, v92
	v_cvt_pk_bf16_f32 v75, v97, v96
	s_cmp_ge_u32 s42, s36
	s_cbranch_scc1 .Lattn_exit
	s_mov_b32 s14, s41
	s_mov_b32 s15, s38
	s_mov_b32 s41, s45
	s_mov_b32 s38, s44
	s_mov_b32 s44, s40
	s_mov_b32 s40, s43
	s_mov_b32 s46, s42
	s_add_i32 s42, s46, 4
	s_min_u32 s43, s42, s37
	s_add_i32 s42, s46, 2
	s_min_u32 s45, s42, s37
	s_mulk_i32 s43, 0x3000
	s_add_u32 s48, s10, s43
	s_addc_u32 s49, s11, 0
	s_lshl_b32 s43, s45, 13
	s_add_u32 s50, s12, s43
	s_addc_u32 s51, s13, 0
	s_add_i32 m0, s22, s38
	s_and_b64 s[52:53], s[4:5], exec
	s_waitcnt vmcnt(3) lgkmcnt(0)
	s_barrier
	s_branch .LBB0_999

; __device__ __forceinline__ void ph_attn(Frame& F) {
;     ...
;         AT_PVMM(vf);
;         if (AT_PRIO) __builtin_amdgcn_s_setprio(0);
;     ...
;         l_run += __shfl_xor(l_run, 32);
;         if (hi == 0) wsf[r32] = 1.0f / l_run;
.LBB0_1011:
	v_mfma_f32_32x32x16_bf16 v[20:35], v[80:83], v[164:167], v[20:35]
	v_mfma_f32_32x32x16_bf16 v[4:19], v[80:83], v[180:183], v[4:19]
	v_mfma_f32_32x32x16_bf16 v[20:35], v[76:79], v[156:159], v[20:35]
	v_mfma_f32_32x32x16_bf16 v[4:19], v[76:79], v[176:179], v[4:19]
	v_mfma_f32_32x32x16_bf16 v[20:35], v[72:75], v[152:155], v[20:35]
	v_mfma_f32_32x32x16_bf16 v[4:19], v[72:75], v[148:151], v[4:19]
	s_setprio 0
	v_and_b32_e32 v36, 64, v208
	v_xor_b32_e32 v2, 32, v208
	v_add_u32_e32 v36, 64, v36
	v_cmp_lt_i32_e32 vcc, v2, v36
	s_nop 1
	v_cndmask_b32_e32 v2, v208, v2, vcc
	v_lshlrev_b32_e32 v2, 2, v2
	ds_bpermute_b32 v2, v2, v209
	s_and_saveexec_b64 s[10:11], s[2:3]
	s_cbranch_execz .LBB0_984
	s_waitcnt lgkmcnt(0)
	v_add_f32_e32 v2, v209, v2
	v_div_scale_f32 v36, s[12:13], v2, v2, 1.0
	v_rcp_f32_e32 v37, v36
	v_div_scale_f32 v38, vcc, 1.0, v2, 1.0
	v_fma_f32 v39, -v36, v37, 1.0
	v_fmac_f32_e32 v37, v39, v37
	v_mul_f32_e32 v39, v38, v37
	v_fma_f32 v40, -v36, v39, v38
	v_fmac_f32_e32 v39, v40, v37
	v_fma_f32 v36, -v36, v39, v38
	v_div_fmas_f32 v36, v36, v37, v39
	v_div_fixup_f32 v2, v36, v2, 1.0
	ds_write_b32 v202, v2
	s_branch .LBB0_984
